# static s_setprio 1 for waves 4-7 in attention A/D loops; s_setprio 1 around the 16-MFMA M phase of the GEMM K-loops
# speedup vs baseline: 1.0237x; 1.0012x over previous
.LBB0_102:
	s_setprio 1
	v_mfma_f32_32x32x16_bf16 v[112:127], v[172:175], v[156:159], v[112:127]
	v_mfma_f32_32x32x16_bf16 v[96:111], v[172:175], v[152:155], v[96:111]
	v_mfma_f32_32x32x16_bf16 v[80:95], v[168:171], v[156:159], v[80:95]
	v_mfma_f32_32x32x16_bf16 v[64:79], v[168:171], v[152:155], v[64:79]
	v_mfma_f32_32x32x16_bf16 v[48:63], v[164:167], v[156:159], v[48:63]
	v_mfma_f32_32x32x16_bf16 v[32:47], v[164:167], v[152:155], v[32:47]
	v_mfma_f32_32x32x16_bf16 v[16:31], v[160:163], v[156:159], v[16:31]
	v_mfma_f32_32x32x16_bf16 v[0:15], v[160:163], v[152:155], v[0:15]
	v_mfma_f32_32x32x16_bf16 v[112:127], v[148:151], v[132:135], v[112:127]
	v_mfma_f32_32x32x16_bf16 v[96:111], v[148:151], v[128:131], v[96:111]
	v_mfma_f32_32x32x16_bf16 v[80:95], v[144:147], v[132:135], v[80:95]
	v_mfma_f32_32x32x16_bf16 v[64:79], v[144:147], v[128:131], v[64:79]
	v_mfma_f32_32x32x16_bf16 v[48:63], v[140:143], v[132:135], v[48:63]
	v_mfma_f32_32x32x16_bf16 v[32:47], v[140:143], v[128:131], v[32:47]
	v_mfma_f32_32x32x16_bf16 v[16:31], v[136:139], v[132:135], v[16:31]
	v_mfma_f32_32x32x16_bf16 v[0:15], v[136:139], v[128:131], v[0:15]
	s_setprio 0
	s_cmp_gt_i32 s19, 0x17fff
	s_cselect_b32 s8, s27, 0x8000
	s_add_i32 s19, s8, s19
	s_add_i32 s18, s18, 1
	s_add_u32 s6, s6, 64
	s_barrier
	s_addc_u32 s7, s7, 0
	s_cmpk_eq_i32 s6, 0x1600
	s_cbranch_scc1 .LBB0_104
	s_branch .LBB0_98

.LBB0_127:
	s_setprio 1
	v_mfma_f32_32x32x16_bf16 v[112:127], v[172:175], v[156:159], v[112:127]
	v_mfma_f32_32x32x16_bf16 v[96:111], v[172:175], v[152:155], v[96:111]
	v_mfma_f32_32x32x16_bf16 v[80:95], v[168:171], v[156:159], v[80:95]
	v_mfma_f32_32x32x16_bf16 v[64:79], v[168:171], v[152:155], v[64:79]
	v_mfma_f32_32x32x16_bf16 v[48:63], v[164:167], v[156:159], v[48:63]
	v_mfma_f32_32x32x16_bf16 v[32:47], v[164:167], v[152:155], v[32:47]
	v_mfma_f32_32x32x16_bf16 v[16:31], v[160:163], v[156:159], v[16:31]
	v_mfma_f32_32x32x16_bf16 v[0:15], v[160:163], v[152:155], v[0:15]
	v_mfma_f32_32x32x16_bf16 v[112:127], v[148:151], v[132:135], v[112:127]
	v_mfma_f32_32x32x16_bf16 v[96:111], v[148:151], v[128:131], v[96:111]
	v_mfma_f32_32x32x16_bf16 v[80:95], v[144:147], v[132:135], v[80:95]
	v_mfma_f32_32x32x16_bf16 v[64:79], v[144:147], v[128:131], v[64:79]
	v_mfma_f32_32x32x16_bf16 v[48:63], v[140:143], v[132:135], v[48:63]
	v_mfma_f32_32x32x16_bf16 v[32:47], v[140:143], v[128:131], v[32:47]
	v_mfma_f32_32x32x16_bf16 v[16:31], v[136:139], v[132:135], v[16:31]
	v_mfma_f32_32x32x16_bf16 v[0:15], v[136:139], v[128:131], v[0:15]
	s_setprio 0
	s_cmp_gt_i32 s18, 0x17fff
	s_cselect_b32 s6, s27, 0x8000
	s_add_i32 s18, s6, s18
	s_add_i32 s17, s17, 1
	s_add_u32 s4, s4, 64
	s_barrier
	s_addc_u32 s5, s5, 0
	s_cmpk_eq_i32 s4, 0x800
	s_cbranch_scc1 .LBB0_129
	s_branch .LBB0_123

.LBB0_299:
	s_setprio 1
	v_mfma_f32_32x32x16_bf16 v[112:127], v[172:175], v[156:159], v[112:127]
	v_mfma_f32_32x32x16_bf16 v[96:111], v[172:175], v[152:155], v[96:111]
	v_mfma_f32_32x32x16_bf16 v[80:95], v[168:171], v[156:159], v[80:95]
	v_mfma_f32_32x32x16_bf16 v[64:79], v[168:171], v[152:155], v[64:79]
	v_mfma_f32_32x32x16_bf16 v[48:63], v[164:167], v[156:159], v[48:63]
	v_mfma_f32_32x32x16_bf16 v[32:47], v[164:167], v[152:155], v[32:47]
	v_mfma_f32_32x32x16_bf16 v[16:31], v[160:163], v[156:159], v[16:31]
	v_mfma_f32_32x32x16_bf16 v[0:15], v[160:163], v[152:155], v[0:15]
	v_mfma_f32_32x32x16_bf16 v[112:127], v[148:151], v[132:135], v[112:127]
	v_mfma_f32_32x32x16_bf16 v[96:111], v[148:151], v[128:131], v[96:111]
	v_mfma_f32_32x32x16_bf16 v[80:95], v[144:147], v[132:135], v[80:95]
	v_mfma_f32_32x32x16_bf16 v[64:79], v[144:147], v[128:131], v[64:79]
	v_mfma_f32_32x32x16_bf16 v[48:63], v[140:143], v[132:135], v[48:63]
	v_mfma_f32_32x32x16_bf16 v[32:47], v[140:143], v[128:131], v[32:47]
	v_mfma_f32_32x32x16_bf16 v[16:31], v[136:139], v[132:135], v[16:31]
	v_mfma_f32_32x32x16_bf16 v[0:15], v[136:139], v[128:131], v[0:15]
	s_setprio 0
	s_cmp_gt_i32 s29, 0x17fff
	s_cselect_b32 s6, s27, 0x8000
	s_add_i32 s29, s6, s29
	s_add_i32 s19, s19, 1
	s_add_u32 s4, s4, 64
	s_barrier
	s_addc_u32 s5, s5, 0
	s_cmpk_eq_i32 s4, 0x800
	s_cbranch_scc1 .LBB0_301
	s_branch .LBB0_295

.LBB0_441:
	v_mov_b32_e32 v184, s28
	v_mov_b32_e32 v185, s28
	v_mov_b32_e32 v186, s28
	v_mov_b32_e32 v187, s28
	v_add_u32_e32 v173, v173, v174
	s_mov_b32 s29, s28
	s_mov_b32 s30, s28
	s_mov_b32 s31, s28
	v_readfirstlane_b32 s8, v190
	s_nop 3
	s_cmp_lt_u32 s8, 0x100
	s_cbranch_scc1 .Lat_d_top
	s_setprio 1

.Lat_d_st0:
	v_mfma_f32_32x32x16_bf16 v[32:47], v[184:187], v[104:107], v[32:47]
	s_mov_b64 s[2:3], 0x160000
	v_readlane_b32 s20, v255, 38
	v_lshl_add_u64 v[164:165], v[164:165], 0, s[2:3]
	v_lshl_add_u64 v[166:167], v[166:167], 0, s[2:3]
	v_lshl_add_u64 v[168:169], v[168:169], 0, s[2:3]
	v_lshl_add_u64 v[170:171], v[170:171], 0, s[2:3]
	v_readlane_b32 s21, v255, 39
	s_add_i32 s10, s10, 2
	s_waitcnt lgkmcnt(0)
	s_barrier
	s_cmp_lt_u32 s10, 64
	s_cbranch_scc1 .Lat_d_top
	s_setprio 0
	s_branch .LBB0_464

.LBB0_468:
	v_mov_b32_e32 v178, s28
	v_mov_b32_e32 v179, s28
	v_mov_b32_e32 v180, s28
	v_mov_b32_e32 v181, s28
	v_add_u32_e32 v173, v167, v166
	s_mov_b32 s29, s28
	s_mov_b32 s30, s28
	s_mov_b32 s31, s28
	v_readfirstlane_b32 s8, v190
	s_nop 3
	s_cmp_lt_u32 s8, 0x100
	s_cbranch_scc1 .Lat_a_top
	s_setprio 1

.Lat_a_st0:
	v_mfma_f32_32x32x16_bf16 v[32:47], v[178:181], v[104:107], v[32:47]
	s_mov_b64 s[2:3], 0x160000
	v_readlane_b32 s20, v255, 38
	v_lshl_add_u64 v[154:155], v[154:155], 0, s[2:3]
	v_lshl_add_u64 v[156:157], v[156:157], 0, s[2:3]
	v_lshl_add_u64 v[158:159], v[158:159], 0, s[2:3]
	v_lshl_add_u64 v[160:161], v[160:161], 0, s[2:3]
	v_readlane_b32 s21, v255, 39
	s_add_i32 s11, s11, 2
	s_waitcnt lgkmcnt(0)
	s_barrier
	s_cmp_lt_u32 s11, 64
	s_cbranch_scc1 .Lat_a_top
	s_setprio 0
	s_branch .LBB0_491
